# speedup vs baseline: 1.0472x; 1.0023x over previous
; DI unsigned pack2(float a, float b) { v2f f = {a, b}; return __builtin_bit_cast(unsigned, __builtin_convertvector(f, v2bf)); }
; DI float bflo(unsigned v) { return __uint_as_float(v << 16); }
; DI float bfhi(unsigned v) { return __uint_as_float(v & 0xffff0000u); }
; DI int lbid() { int x = blockIdx.x; asm volatile("" : "+s"(x)); return x; }
; DI void cmp2_phase(const Params& p) {
;     ...
;   for (int task = lbid(); task < 2048; task += gridDim.x) {
;     const int c = task >> 10, m = (task & 1023) * 4 + rr;
;     const u16* hrow = p.h1 + ((long)c * 4096 + m) * 256;
;     const float* w2 = p.a_w2_k; if (c) w2 = p.a_w2_v;
;     float s = 0.f;
;     for (int k = 0; k < 256; k += 2) {
;       const unsigned hv = *(const unsigned*)(hrow + k);
;       s += bflo(hv) * w2[k * 64 + nn] + bfhi(hv) * w2[(k + 1) * 64 + nn];
;     }
;     if ((m & 511) == 511) s = 0.f;
;     u16* dstp = p.kcmp; if (c) dstp = p.vcmp; dstp += (long)m * 64 + nn;
;     *dstp = (u16)(pack2(s, 0.f) & 0xffffu);
;     if (c == 0) {
;       float ss = s * s;
; #pragma unroll
;       for (int o = 32; o > 0; o >>= 1) ss += __shfl_xor(ss, o);
;       if (nn == 0) atomicMax(p.kmax2 + 480 + (m >> 9), __float_as_uint(ss));
;     }
.LBB0_740:
	global_load_dwordx4 v[20:23], v[8:9], off offset:-28
	global_load_dwordx4 v[24:27], v[8:9], off offset:-12
	global_load_dword v28, v[10:11], off offset:-3840
	global_load_dword v29, v[10:11], off offset:-3584
	global_load_dword v30, v[10:11], off offset:-3328
	global_load_dword v31, v[10:11], off offset:-3072
	global_load_dword v32, v[10:11], off offset:-2816
	global_load_dword v33, v[10:11], off offset:-2560
	global_load_dword v34, v[10:11], off offset:-2304
	global_load_dword v35, v[10:11], off offset:-2048
	global_load_dword v36, v[10:11], off offset:-1792
	global_load_dword v37, v[10:11], off offset:-1536
	global_load_dword v38, v[10:11], off offset:-1280
	global_load_dword v39, v[10:11], off offset:-1024
	global_load_dword v40, v[10:11], off offset:-768
	global_load_dword v41, v[10:11], off offset:-512
	global_load_dword v42, v[10:11], off offset:-256
	global_load_dword v43, v[10:11], off
	s_add_i32 s6, s6, 16
	v_lshl_add_u64 v[10:11], v[10:11], 0, s[10:11]
	v_lshl_add_u64 v[8:9], v[8:9], 0, 32
	s_cmpk_gt_u32 s6, 0xfd
	s_waitcnt vmcnt(17)
	v_lshlrev_b32_e32 v44, 16, v20
	v_and_b32_e32 v45, 0xffff0000, v20
	v_lshlrev_b32_e32 v20, 16, v21
	v_and_b32_e32 v21, 0xffff0000, v21
	s_waitcnt vmcnt(14)
	v_pk_mul_f32 v[28:29], v[28:29], v[44:45]
	v_lshlrev_b32_e32 v46, 16, v22
	v_and_b32_e32 v47, 0xffff0000, v22
	s_waitcnt vmcnt(12)
	v_pk_mul_f32 v[20:21], v[30:31], v[20:21]
	v_add_f32_e32 v28, v28, v29
	v_lshlrev_b32_e32 v22, 16, v23
	v_and_b32_e32 v23, 0xffff0000, v23
	s_waitcnt vmcnt(10)
	v_pk_mul_f32 v[30:31], v[32:33], v[46:47]
	v_add_f32_e32 v20, v20, v21
	v_add_f32_e32 v19, v19, v28
	v_lshlrev_b32_e32 v48, 16, v24
	v_and_b32_e32 v49, 0xffff0000, v24
	s_waitcnt vmcnt(8)
	v_pk_mul_f32 v[22:23], v[34:35], v[22:23]
	v_add_f32_e32 v21, v30, v31
	v_add_f32_e32 v19, v19, v20
	v_lshlrev_b32_e32 v24, 16, v25
	v_and_b32_e32 v25, 0xffff0000, v25
	s_waitcnt vmcnt(6)
	v_pk_mul_f32 v[32:33], v[36:37], v[48:49]
	v_add_f32_e32 v22, v22, v23
	v_add_f32_e32 v19, v19, v21
	v_lshlrev_b32_e32 v50, 16, v26
	v_and_b32_e32 v51, 0xffff0000, v26
	s_waitcnt vmcnt(4)
	v_pk_mul_f32 v[24:25], v[38:39], v[24:25]
	v_add_f32_e32 v23, v32, v33
	v_add_f32_e32 v19, v19, v22
	v_lshlrev_b32_e32 v26, 16, v27
	v_and_b32_e32 v27, 0xffff0000, v27
	s_waitcnt vmcnt(2)
	v_pk_mul_f32 v[34:35], v[40:41], v[50:51]
	v_add_f32_e32 v24, v24, v25
	v_add_f32_e32 v19, v19, v23
	s_waitcnt vmcnt(0)
	v_pk_mul_f32 v[26:27], v[42:43], v[26:27]
	v_add_f32_e32 v25, v34, v35
	v_add_f32_e32 v19, v19, v24
	v_add_f32_e32 v26, v26, v27
	v_add_f32_e32 v19, v19, v25
	v_add_f32_e32 v19, v19, v26
	s_cbranch_scc0 .LBB0_740
	s_lshl_b32 s6, s12, 2
	s_and_b32 s6, s6, 0xffc
	s_and_b64 vcc, s[0:1], exec
	s_cselect_b32 s0, s17, 0x158
	s_add_u32 s0, s56, s0
	s_addc_u32 s1, s57, 0
	s_load_dwordx2 s[0:1], s[0:1], 0x0
	v_add_u32_e32 v8, s6, v0
	v_ashrrev_i32_e32 v9, 31, v8
	v_and_b32_e32 v10, 0x1ff, v8
	v_cmp_ne_u32_e64 s[6:7], s16, v10
	v_lshlrev_b64 v[20:21], 7, v[8:9]
	s_waitcnt lgkmcnt(0)
	v_lshl_add_u64 v[20:21], s[0:1], 0, v[20:21]
	v_cndmask_b32_e64 v10, 0, v19, s[6:7]
	v_lshl_add_u64 v[20:21], v[20:21], 0, v[6:7]
	v_cvt_pk_bf16_f32 v9, v10, s0
	global_store_short v[20:21], v9, off
	s_cbranch_vccz .LBB0_738
	v_cmp_lt_i32_e32 vcc, v13, v12
	v_mul_f32_e32 v9, v10, v10
	s_nop 0
	v_cndmask_b32_e32 v11, v1, v13, vcc
	v_lshlrev_b32_e32 v11, 2, v11
	ds_bpermute_b32 v9, v11, v9
	v_cmp_lt_i32_e32 vcc, v14, v12
	s_waitcnt lgkmcnt(0)
	v_fmac_f32_e32 v9, v10, v10
	v_cndmask_b32_e32 v11, v1, v14, vcc
	v_lshlrev_b32_e32 v10, 2, v11
	ds_bpermute_b32 v10, v10, v9
	v_cmp_lt_i32_e32 vcc, v15, v12
	s_waitcnt lgkmcnt(0)
	v_add_f32_e32 v9, v9, v10
	v_cndmask_b32_e32 v11, v1, v15, vcc
	v_lshlrev_b32_e32 v11, 2, v11
	ds_bpermute_b32 v10, v11, v9
	v_cmp_lt_i32_e32 vcc, v16, v12
	s_waitcnt lgkmcnt(0)
	v_add_f32_e32 v9, v9, v10
	v_cndmask_b32_e32 v11, v1, v16, vcc
	v_lshlrev_b32_e32 v11, 2, v11
	ds_bpermute_b32 v10, v11, v9
	v_cmp_lt_i32_e32 vcc, v17, v12
	s_waitcnt lgkmcnt(0)
	v_add_f32_e32 v9, v9, v10
	v_cndmask_b32_e32 v11, v1, v17, vcc
	v_lshlrev_b32_e32 v11, 2, v11
	ds_bpermute_b32 v10, v11, v9
	v_cmp_lt_i32_e32 vcc, v18, v12
	s_waitcnt lgkmcnt(0)
	v_add_f32_e32 v9, v9, v10
	v_cndmask_b32_e32 v11, v1, v18, vcc
	v_lshlrev_b32_e32 v10, 2, v11
	ds_bpermute_b32 v10, v10, v9
	s_and_saveexec_b64 s[0:1], s[4:5]
	s_cbranch_execz .LBB0_737
	v_ashrrev_i32_e32 v20, 9, v8
	v_ashrrev_i32_e32 v21, 31, v20
	s_waitcnt lgkmcnt(0)
	v_add_f32_e32 v10, v9, v10
	v_lshl_add_u64 v[8:9], v[20:21], 2, s[2:3]
	global_load_dword v20, v[8:9], off offset:1920 sc1
	s_waitcnt vmcnt(0)
	v_cmp_gt_u32_e32 vcc, v10, v20
	s_and_b64 exec, exec, vcc
	s_cbranch_execz .LBB0_737
	global_atomic_umax v[8:9], v10, off offset:1920
	s_branch .LBB0_737

; DI unsigned pack2(float a, float b) { v2f f = {a, b}; return __builtin_bit_cast(unsigned, __builtin_convertvector(f, v2bf)); }
; DI void diff_attn_phase(const Params& p, char* smem) {
;     ...
;     if (mm == 1) {
; #pragma unroll
;       for (int dc = 0; dc < 4; ++dc)
; #pragma unroll
;         for (int g4 = 0; g4 < 4; ++g4) {
;           u32x2 o;
;           o.x = pack2(ot[dc][4 * g4] * rl, ot[dc][4 * g4 + 1] * rl);
;           o.y = pack2(ot[dc][4 * g4 + 2] * rl, ot[dc][4 * g4 + 3] * rl);
;           *(u32x2*)(obase + 32 * dc + 8 * g4) = o;
;         }
;       asm volatile("s_waitcnt vmcnt(0)" ::: "memory");
;       __syncthreads();
;       if (tid == 0) {
;         __builtin_amdgcn_fence(__ATOMIC_RELEASE, "agent");
;         asm volatile("s_waitcnt vmcnt(0)" ::: "memory");
;         __hip_atomic_store(p.pflag + pair, 1u, __ATOMIC_RELAXED, __HIP_MEMORY_SCOPE_AGENT);
;       }
;       continue;
.LBB0_1513:
	s_and_b64 vcc, exec, s[0:1]
	s_cbranch_vccz .LBB0_1473
	v_pk_mul_f32 v[2:3], v[64:65], v[6:7] op_sel_hi:[1,0]
	v_pk_mul_f32 v[4:5], v[66:67], v[6:7] op_sel_hi:[1,0]
	v_cvt_pk_bf16_f32 v2, v2, v3
	v_cvt_pk_bf16_f32 v3, v4, v5
	global_store_dwordx2 v[8:9], v[2:3], off sc0 sc1
	v_pk_mul_f32 v[2:3], v[68:69], v[6:7] op_sel_hi:[1,0]
	v_pk_mul_f32 v[4:5], v[70:71], v[6:7] op_sel_hi:[1,0]
	v_cvt_pk_bf16_f32 v2, v2, v3
	v_cvt_pk_bf16_f32 v3, v4, v5
	global_store_dwordx2 v[8:9], v[2:3], off offset:16 sc0 sc1
	v_pk_mul_f32 v[2:3], v[72:73], v[6:7] op_sel_hi:[1,0]
	v_pk_mul_f32 v[4:5], v[74:75], v[6:7] op_sel_hi:[1,0]
	v_cvt_pk_bf16_f32 v2, v2, v3
	v_cvt_pk_bf16_f32 v3, v4, v5
	global_store_dwordx2 v[8:9], v[2:3], off offset:32 sc0 sc1
	v_pk_mul_f32 v[2:3], v[76:77], v[6:7] op_sel_hi:[1,0]
	v_pk_mul_f32 v[4:5], v[78:79], v[6:7] op_sel_hi:[1,0]
	v_cvt_pk_bf16_f32 v2, v2, v3
	v_cvt_pk_bf16_f32 v3, v4, v5
	global_store_dwordx2 v[8:9], v[2:3], off offset:48 sc0 sc1
	v_pk_mul_f32 v[2:3], v[48:49], v[6:7] op_sel_hi:[1,0]
	v_pk_mul_f32 v[4:5], v[50:51], v[6:7] op_sel_hi:[1,0]
	v_cvt_pk_bf16_f32 v2, v2, v3
	v_cvt_pk_bf16_f32 v3, v4, v5
	global_store_dwordx2 v[8:9], v[2:3], off offset:64 sc0 sc1
	v_pk_mul_f32 v[2:3], v[52:53], v[6:7] op_sel_hi:[1,0]
	v_pk_mul_f32 v[4:5], v[54:55], v[6:7] op_sel_hi:[1,0]
	v_cvt_pk_bf16_f32 v2, v2, v3
	v_cvt_pk_bf16_f32 v3, v4, v5
	global_store_dwordx2 v[8:9], v[2:3], off offset:80 sc0 sc1
	v_pk_mul_f32 v[2:3], v[56:57], v[6:7] op_sel_hi:[1,0]
	v_pk_mul_f32 v[4:5], v[58:59], v[6:7] op_sel_hi:[1,0]
	v_cvt_pk_bf16_f32 v2, v2, v3
	v_cvt_pk_bf16_f32 v3, v4, v5
	global_store_dwordx2 v[8:9], v[2:3], off offset:96 sc0 sc1
	v_pk_mul_f32 v[2:3], v[60:61], v[6:7] op_sel_hi:[1,0]
	v_pk_mul_f32 v[4:5], v[62:63], v[6:7] op_sel_hi:[1,0]
	v_cvt_pk_bf16_f32 v2, v2, v3
	v_cvt_pk_bf16_f32 v3, v4, v5
	global_store_dwordx2 v[8:9], v[2:3], off offset:112 sc0 sc1
	v_pk_mul_f32 v[2:3], v[32:33], v[6:7] op_sel_hi:[1,0]
	v_pk_mul_f32 v[4:5], v[34:35], v[6:7] op_sel_hi:[1,0]
	v_cvt_pk_bf16_f32 v2, v2, v3
	v_cvt_pk_bf16_f32 v3, v4, v5
	global_store_dwordx2 v[8:9], v[2:3], off offset:128 sc0 sc1
	v_pk_mul_f32 v[2:3], v[36:37], v[6:7] op_sel_hi:[1,0]
	v_pk_mul_f32 v[4:5], v[38:39], v[6:7] op_sel_hi:[1,0]
	v_cvt_pk_bf16_f32 v2, v2, v3
	v_cvt_pk_bf16_f32 v3, v4, v5
	global_store_dwordx2 v[8:9], v[2:3], off offset:144 sc0 sc1
	v_pk_mul_f32 v[2:3], v[40:41], v[6:7] op_sel_hi:[1,0]
	v_pk_mul_f32 v[4:5], v[42:43], v[6:7] op_sel_hi:[1,0]
	v_cvt_pk_bf16_f32 v2, v2, v3
	v_cvt_pk_bf16_f32 v3, v4, v5
	global_store_dwordx2 v[8:9], v[2:3], off offset:160 sc0 sc1
	v_pk_mul_f32 v[2:3], v[44:45], v[6:7] op_sel_hi:[1,0]
	v_pk_mul_f32 v[4:5], v[46:47], v[6:7] op_sel_hi:[1,0]
	v_cvt_pk_bf16_f32 v2, v2, v3
	v_cvt_pk_bf16_f32 v3, v4, v5
	global_store_dwordx2 v[8:9], v[2:3], off offset:176 sc0 sc1
	v_pk_mul_f32 v[2:3], v[16:17], v[6:7] op_sel_hi:[1,0]
	v_pk_mul_f32 v[4:5], v[18:19], v[6:7] op_sel_hi:[1,0]
	v_cvt_pk_bf16_f32 v2, v2, v3
	v_cvt_pk_bf16_f32 v3, v4, v5
	global_store_dwordx2 v[8:9], v[2:3], off offset:192 sc0 sc1
	v_pk_mul_f32 v[2:3], v[20:21], v[6:7] op_sel_hi:[1,0]
	v_pk_mul_f32 v[4:5], v[22:23], v[6:7] op_sel_hi:[1,0]
	v_cvt_pk_bf16_f32 v2, v2, v3
	v_cvt_pk_bf16_f32 v3, v4, v5
	global_store_dwordx2 v[8:9], v[2:3], off offset:208 sc0 sc1
	v_pk_mul_f32 v[2:3], v[24:25], v[6:7] op_sel_hi:[1,0]
	v_pk_mul_f32 v[4:5], v[26:27], v[6:7] op_sel_hi:[1,0]
	v_cvt_pk_bf16_f32 v2, v2, v3
	v_cvt_pk_bf16_f32 v3, v4, v5
	global_store_dwordx2 v[8:9], v[2:3], off offset:224 sc0 sc1
	v_pk_mul_f32 v[2:3], v[28:29], v[6:7] op_sel_hi:[1,0]
	v_pk_mul_f32 v[4:5], v[30:31], v[6:7] op_sel_hi:[1,0]
	v_cvt_pk_bf16_f32 v2, v2, v3
	v_cvt_pk_bf16_f32 v3, v4, v5
	global_store_dwordx2 v[8:9], v[2:3], off offset:240 sc0 sc1
	s_waitcnt vmcnt(0)
	v_cmp_eq_u32_e32 vcc, 0, v154
	s_waitcnt vmcnt(0) lgkmcnt(0)
	s_barrier
	s_and_saveexec_b64 s[0:1], vcc
	s_xor_b64 s[0:1], exec, s[0:1]
	s_cbranch_execz .LBB0_1472
	s_ashr_i32 s93, s92, 31
	s_waitcnt vmcnt(0)
	s_lshl_b64 s[4:5], s[92:93], 2
	s_add_u32 s4, s20, s4
	s_addc_u32 s5, s21, s5
	global_store_dword v1, v151, s[4:5] sc1
	s_branch .LBB0_1472
